# phase-1 copier stop threshold re-tuned to 731 tiles after the phase-4 epilogue rewrite
# speedup vs baseline: 1.0471x; 1.0036x over previous
.Lcp1_entry:
	v_readfirstlane_b32 s0, v192
	v_lshlrev_b32_e32 v16, 4, v192
	s_add_u32 s4, s38, 0xc7b7100
	s_addc_u32 s5, s39, 0
	s_add_u32 s6, s38, 0xc7b7200
	s_addc_u32 s7, s39, 0
	s_lshr_b32 s0, s0, 6
	s_mov_b32 s1, 0
	s_mov_b32 s30, 2
	v_mov_b32_e32 v93, 0
	v_mov_b32_e32 v94, 1
	v_mov_b32_e32 v95, 16
	v_mov_b32_e32 v96, 20
	v_add_u32_e32 v17, 0x2000, v16
	v_add_u32_e32 v18, 0x4000, v16
	v_add_u32_e32 v19, 0x6000, v16
	v_add_u32_e32 v20, 0x8000, v16
	v_add_u32_e32 v21, 0xa000, v16
	v_add_u32_e32 v22, 0xc000, v16
	v_add_u32_e32 v23, 0xe000, v16
	v_add_u32_e32 v104, 0x10000, v16
	v_add_u32_e32 v105, 0x12000, v16
	v_add_u32_e32 v106, 0x14000, v16
	v_add_u32_e32 v107, 0x16000, v16
	v_add_u32_e32 v108, 0x18000, v16
	v_add_u32_e32 v109, 0x1a000, v16
	v_add_u32_e32 v110, 0x1c000, v16
	v_add_u32_e32 v111, 0x1e000, v16
	s_barrier
	s_cmp_lg_u32 s0, 0
	s_cbranch_scc1 .Lcp1_p0
	s_mov_b64 s[22:23], exec
	s_mov_b64 exec, 1
	global_load_dword v118, v93, s[6:7] sc1
	v_mov_b32_e32 v117, 0xa80
	s_waitcnt vmcnt(0)
	v_readfirstlane_b32 s25, v118
	s_cmpk_gt_u32 s25, 0x2da
	s_cbranch_scc1 .Lcp1_pnone
	v_mov_b32_e32 v117, 2
	global_atomic_add v117, v93, v117, s[4:5] sc0
	s_waitcnt vmcnt(0)

.Lcp1_ac_A_j:
	s_lshl_b32 s18, s18, 17
	v_add_u32_e32 v92, s24, v16
	s_add_u32 s14, s36, s19
	s_addc_u32 s15, s37, 0
	s_add_u32 s14, s14, s18
	s_addc_u32 s15, s15, 0
	s_add_u32 s12, s12, s18
	s_addc_u32 s13, s13, 0
	s_add_u32 s12, s12, 0x2000
	s_addc_u32 s13, s13, 0
	global_load_dwordx4 v[180:183], v16, s[12:13] nt
	global_load_dwordx4 v[184:187], v17, s[12:13] nt
	global_load_dwordx4 v[188:191], v18, s[12:13] nt
	global_load_dwordx4 v[196:199], v19, s[12:13] nt
	global_load_dwordx4 v[200:203], v20, s[12:13] nt
	global_load_dwordx4 v[204:207], v21, s[12:13] nt
	global_load_dwordx4 v[208:211], v22, s[12:13] nt
	global_load_dwordx4 v[212:215], v23, s[12:13] nt
	global_load_dwordx4 v[216:219], v104, s[12:13] nt
	global_load_dwordx4 v[220:223], v105, s[12:13] nt
	global_load_dwordx4 v[224:227], v106, s[12:13] nt
	global_load_dwordx4 v[228:231], v107, s[12:13] nt
	global_load_dwordx4 v[244:247], v108, s[12:13] nt
	global_load_dwordx4 v[248:251], v109, s[12:13] nt
	global_load_dwordx4 v[4:7], v110, s[12:13] nt
	global_load_dwordx4 v[8:11], v92, s[12:13] nt
	s_waitcnt vmcnt(31)
	global_store_dwordx4 v16, v[30:33], s[10:11] nt
	s_waitcnt vmcnt(31)
	global_store_dwordx4 v17, v[34:37], s[10:11] nt
	s_waitcnt vmcnt(31)
	global_store_dwordx4 v18, v[38:41], s[10:11] nt
	s_waitcnt vmcnt(31)
	global_store_dwordx4 v19, v[42:45], s[10:11] nt
	s_waitcnt vmcnt(31)
	global_store_dwordx4 v20, v[46:49], s[10:11] nt
	s_waitcnt vmcnt(31)
	global_store_dwordx4 v21, v[50:53], s[10:11] nt
	s_waitcnt vmcnt(31)
	global_store_dwordx4 v22, v[54:57], s[10:11] nt
	s_waitcnt vmcnt(31)
	global_store_dwordx4 v23, v[58:61], s[10:11] nt
	s_waitcnt vmcnt(31)
	global_store_dwordx4 v104, v[62:65], s[10:11] nt
	s_waitcnt vmcnt(31)
	global_store_dwordx4 v105, v[66:69], s[10:11] nt
	s_waitcnt vmcnt(31)
	global_store_dwordx4 v106, v[70:73], s[10:11] nt
	s_waitcnt vmcnt(31)
	global_store_dwordx4 v107, v[74:77], s[10:11] nt
	s_waitcnt vmcnt(31)
	global_store_dwordx4 v108, v[164:167], s[10:11] nt
	s_waitcnt vmcnt(31)
	global_store_dwordx4 v109, v[168:171], s[10:11] nt
	s_waitcnt vmcnt(31)
	global_store_dwordx4 v110, v[172:175], s[10:11] nt
	s_waitcnt vmcnt(31)
	global_store_dwordx4 v91, v[176:179], s[10:11] nt
	s_cmp_lg_u32 s0, 0
	s_cbranch_scc1 .Lcp1_A_s4
	s_mov_b64 s[22:23], exec
	s_mov_b64 exec, 1
	s_cmp_lg_u32 s1, 0
	s_cbranch_scc1 .Lcp1_A_s4stop
	s_waitcnt vmcnt(32)
	v_readfirstlane_b32 s25, v118
	s_cmpk_gt_u32 s25, 0x2da
	s_cselect_b32 s1, 1, 0
	v_readfirstlane_b32 s26, v117
	s_cmpk_ge_u32 s26, 0xa80
	s_cselect_b32 s27, 1, 0
	s_or_b32 s1, s1, s27
	s_branch .Lcp1_A_s4pub

.Lcp1_ac_B_j:
	s_lshl_b32 s18, s18, 17
	v_add_u32_e32 v91, s24, v16
	s_add_u32 s10, s36, s19
	s_addc_u32 s11, s37, 0
	s_add_u32 s10, s10, s18
	s_addc_u32 s11, s11, 0
	s_add_u32 s8, s8, s18
	s_addc_u32 s9, s9, 0
	s_add_u32 s8, s8, 0x2000
	s_addc_u32 s9, s9, 0
	global_load_dwordx4 v[30:33], v16, s[8:9] nt
	global_load_dwordx4 v[34:37], v17, s[8:9] nt
	global_load_dwordx4 v[38:41], v18, s[8:9] nt
	global_load_dwordx4 v[42:45], v19, s[8:9] nt
	global_load_dwordx4 v[46:49], v20, s[8:9] nt
	global_load_dwordx4 v[50:53], v21, s[8:9] nt
	global_load_dwordx4 v[54:57], v22, s[8:9] nt
	global_load_dwordx4 v[58:61], v23, s[8:9] nt
	global_load_dwordx4 v[62:65], v104, s[8:9] nt
	global_load_dwordx4 v[66:69], v105, s[8:9] nt
	global_load_dwordx4 v[70:73], v106, s[8:9] nt
	global_load_dwordx4 v[74:77], v107, s[8:9] nt
	global_load_dwordx4 v[164:167], v108, s[8:9] nt
	global_load_dwordx4 v[168:171], v109, s[8:9] nt
	global_load_dwordx4 v[172:175], v110, s[8:9] nt
	global_load_dwordx4 v[176:179], v91, s[8:9] nt
	s_waitcnt vmcnt(31)
	global_store_dwordx4 v16, v[180:183], s[14:15] nt
	s_waitcnt vmcnt(31)
	global_store_dwordx4 v17, v[184:187], s[14:15] nt
	s_waitcnt vmcnt(31)
	global_store_dwordx4 v18, v[188:191], s[14:15] nt
	s_waitcnt vmcnt(31)
	global_store_dwordx4 v19, v[196:199], s[14:15] nt
	s_waitcnt vmcnt(31)
	global_store_dwordx4 v20, v[200:203], s[14:15] nt
	s_waitcnt vmcnt(31)
	global_store_dwordx4 v21, v[204:207], s[14:15] nt
	s_waitcnt vmcnt(31)
	global_store_dwordx4 v22, v[208:211], s[14:15] nt
	s_waitcnt vmcnt(31)
	global_store_dwordx4 v23, v[212:215], s[14:15] nt
	s_waitcnt vmcnt(31)
	global_store_dwordx4 v104, v[216:219], s[14:15] nt
	s_waitcnt vmcnt(31)
	global_store_dwordx4 v105, v[220:223], s[14:15] nt
	s_waitcnt vmcnt(31)
	global_store_dwordx4 v106, v[224:227], s[14:15] nt
	s_waitcnt vmcnt(31)
	global_store_dwordx4 v107, v[228:231], s[14:15] nt
	s_waitcnt vmcnt(31)
	global_store_dwordx4 v108, v[244:247], s[14:15] nt
	s_waitcnt vmcnt(31)
	global_store_dwordx4 v109, v[248:251], s[14:15] nt
	s_waitcnt vmcnt(31)
	global_store_dwordx4 v110, v[4:7], s[14:15] nt
	s_waitcnt vmcnt(31)
	global_store_dwordx4 v92, v[8:11], s[14:15] nt
	s_cmp_lg_u32 s0, 0
	s_cbranch_scc1 .Lcp1_B_s4
	s_mov_b64 s[22:23], exec
	s_mov_b64 exec, 1
	s_cmp_lg_u32 s1, 0
	s_cbranch_scc1 .Lcp1_B_s4stop
	s_waitcnt vmcnt(32)
	v_readfirstlane_b32 s25, v118
	s_cmpk_gt_u32 s25, 0x2da
	s_cselect_b32 s1, 1, 0
	v_readfirstlane_b32 s26, v117
	s_cmpk_ge_u32 s26, 0xa80
	s_cselect_b32 s27, 1, 0
	s_or_b32 s1, s1, s27
	s_branch .Lcp1_B_s4pub
